# FFN1-gu and FFN2-gu: 14 dedicated converter workgroups run the weight conversions for the whole phase (GEMM tiles strided by 242, same 6 rounds); in-proj keeps last-round tails
# baseline (speedup 1.0000x reference)
.LBB0_29:
	v_mov_b32_e32 v16, v183
	s_cmpk_gt_i32 s4, 0x2da9
	v_readfirstlane_b32 s3, v16
	s_cbranch_scc1 .LBB0_427
	s_cmpk_lt_i32 s4, 0xb00
	s_mov_b32 s5, 1
	s_cbranch_scc1 .LBB0_34
	s_cmpk_gt_u32 s4, 0x15ff
	s_cbranch_scc0 .LBB0_35
	v_readlane_b32 s16, v234, 40
	v_readlane_b32 s22, v234, 46
	v_readlane_b32 s23, v234, 47
	v_readlane_b32 s24, v234, 48
	v_readlane_b32 s25, v234, 49
	s_add_i32 s12, s4, 0xffffea00
	v_readlane_b32 s17, v234, 41
	v_readlane_b32 s18, v234, 42
	v_readlane_b32 s19, v234, 43
	v_readlane_b32 s20, v234, 44
	v_readlane_b32 s21, v234, 45
	v_readlane_b32 s26, v234, 50
	v_readlane_b32 s27, v234, 51
	v_readlane_b32 s28, v234, 52
	v_readlane_b32 s29, v234, 53
	v_readlane_b32 s30, v234, 54
	v_readlane_b32 s31, v234, 55
	s_mov_b64 s[8:9], s[22:23]
	s_mov_b64 s[10:11], s[24:25]
	s_cbranch_execz .LBB0_36
	s_mov_b64 s[6:7], 0x4400000
	s_movk_i32 s28, 0x3a28
	s_mov_b32 s5, 3
	s_branch .LBB0_37

.LBB0_79:
	s_add_i32 s41, s4, s50
	s_cmpk_lt_i32 s41, 0x2daa
	s_cselect_b64 s[10:11], -1, 0
	s_cmpk_gt_i32 s41, 0x2da9
	s_cselect_b64 s[8:9], -1, 0
	s_and_b64 vcc, exec, s[8:9]
	s_mov_b64 s[12:13], s[6:7]
	s_mov_b32 s42, s28
	s_mov_b32 s43, s5
	s_mov_b32 s44, s2
	s_mov_b32 s45, s29
	s_cbranch_vccnz .LBB0_121
	s_cmpk_lt_i32 s41, 0xb00
	s_cbranch_scc1 .LBB0_84
	s_cmpk_gt_u32 s41, 0x15ff
	s_cbranch_scc0 .LBB0_85
	v_readlane_b32 s12, v234, 40
	v_readlane_b32 s14, v234, 42
	v_readlane_b32 s15, v234, 43
	v_readlane_b32 s16, v234, 44
	v_readlane_b32 s17, v234, 45
	v_readlane_b32 s18, v234, 46
	v_readlane_b32 s19, v234, 47
	v_readlane_b32 s20, v234, 48
	v_readlane_b32 s21, v234, 49
	s_add_i32 s3, s41, 0xffffea00
	v_readlane_b32 s13, v234, 41
	v_readlane_b32 s22, v234, 50
	v_readlane_b32 s23, v234, 51
	v_readlane_b32 s24, v234, 52
	v_readlane_b32 s25, v234, 53
	v_readlane_b32 s26, v234, 54
	v_readlane_b32 s27, v234, 55
	s_mov_b64 s[14:15], s[18:19]
	s_mov_b64 s[16:17], s[20:21]
	s_cbranch_execz .LBB0_86
	s_mov_b64 s[12:13], 0x4400000
	s_movk_i32 s42, 0x3a28
	s_mov_b32 s43, 3
	s_branch .LBB0_87

.LBB0_487:
	s_or_b64 exec, exec, s[0:1]
	v_readlane_b32 s0, v234, 0
	v_readlane_b32 s2, v234, 2
	v_readlane_b32 s1, v234, 1
	v_readlane_b32 s3, v234, 3
	s_add_u32 s0, s2, 0x14e00000
	s_addc_u32 s1, s3, 0
	s_add_u32 s10, s2, 0x200000
	s_addc_u32 s11, s3, 0
	v_readlane_b32 s4, v234, 14
	v_writelane_b32 v233, s0, 8
	s_cmpk_lt_i32 s4, 0xf2
	v_mov_b32_e32 v14, v183
	v_writelane_b32 v233, s1, 9
	s_cselect_b64 s[0:1], -1, 0
	s_waitcnt lgkmcnt(0)
	s_barrier
	v_writelane_b32 v233, s0, 10
	s_cmpk_gt_i32 s4, 0xf1
	v_readfirstlane_b32 s2, v14
	v_writelane_b32 v233, s1, 11
	s_cbranch_scc1 .LBB0_511
	s_ashr_i32 s26, s4, 31
	s_lshr_b32 s0, s26, 29
	s_add_i32 s3, s4, s0
	s_and_b32 s0, s3, -8
	s_sub_i32 s5, s4, s0
	s_cmp_gt_i32 s5, 3
	s_cbranch_scc0 .LBB0_490
	s_mul_i32 s0, s5, 0xb5
	s_add_i32 s4, s0, 4
	s_cbranch_execz .LBB0_491
	s_branch .LBB0_492

.LBB0_494:
	v_lshrrev_b32_e32 v16, 1, v14
	v_and_b32_e32 v16, 24, v16
	v_and_b32_e32 v15, 15, v14
	v_lshlrev_b32_e32 v17, 1, v16
	v_lshlrev_b32_e32 v14, 2, v14
	s_sext_i32_i16 s19, s0
	v_lshl_or_b32 v150, s1, 6, v15
	v_lshl_or_b32 v15, v15, 6, v17
	s_lshl_b32 s0, s1, 13
	v_and_b32_e32 v14, 32, v14
	v_bitop3_b32 v17, v15, s0, v14 bitop3:0xde
	s_lshl_b32 s0, s3, 5
	s_mov_b64 s[6:7], 0x80
	s_and_b32 s3, s0, 0x60
	s_add_i32 m0, s28, 0x18000
	v_lshl_add_u64 v[6:7], v[6:7], 0, s[6:7]
	s_lshl_b32 s0, s3, 7
	s_waitcnt vmcnt(2)
	s_barrier
	global_load_lds_dwordx4 v[6:7], off
	v_lshl_add_u64 v[4:5], v[4:5], 0, s[6:7]
	s_add_i32 m0, s28, 0x1a000
	s_add_i32 s34, s28, 0x8000
	s_add_i32 s35, s28, 0xa000
	v_bitop3_b32 v151, v15, s0, v14 bitop3:0xde
	global_load_lds_dwordx4 v[4:5], off
	v_lshl_add_u64 v[0:1], v[0:1], 0, s[6:7]
	s_mov_b32 m0, s34
	s_add_u32 s0, s22, 0x80080
	global_load_lds_dwordx4 v[0:1], off
	v_lshl_add_u64 v[0:1], v[2:3], 0, s[6:7]
	s_mov_b32 m0, s35
	s_addc_u32 s1, s23, 0
	global_load_lds_dwordx4 v[0:1], off
	s_add_i32 m0, s28, 0x1c000
	v_lshl_add_u64 v[0:1], s[0:1], 0, v[130:131]
	global_load_lds_dwordx4 v[0:1], off
	v_lshl_add_u64 v[0:1], s[0:1], 0, v[134:135]
	s_add_i32 m0, s28, 0x1e000
	s_cmpk_lt_u32 s2, 0x100
	global_load_lds_dwordx4 v[0:1], off
	v_lshlrev_b32_e32 v0, 15, v8
	v_and_b32_e32 v0, 0xffff0000, v0
	v_lshl_add_u32 v0, v9, 12, v0
	v_and_b32_e32 v1, 1, v8
	v_lshl_or_b32 v0, v1, 6, v0
	v_lshl_add_u32 v136, v10, 1, v0
	v_lshlrev_b32_e32 v0, 15, v11
	v_and_b32_e32 v0, 0xffff0000, v0
	s_waitcnt vmcnt(6)
	v_lshl_add_u32 v0, v12, 12, v0
	v_and_b32_e32 v1, 1, v11
	s_cselect_b64 s[8:9], -1, 0
	v_readlane_b32 s0, v234, 12
	v_lshl_or_b32 v0, v1, 6, v0
	s_add_i32 s38, 0, 0x10000
	s_add_i32 s39, 0, 0x14000
	s_ashr_i32 s36, s0, 31
	s_movk_i32 s37, 0xf2
	v_or_b32_e32 v152, s3, v16
	v_mov_b32_e32 v137, v131
	v_lshl_add_u32 v138, v13, 1, v0
	v_mov_b32_e32 v139, v131
	v_mov_b64_e32 v[140:141], 0x5ac
	v_mov_b64_e32 v[142:143], 0x5ab
	v_add_u32_e32 v153, s38, v151
	v_add_u32_e32 v154, s39, v151
	v_add_u32_e32 v155, 0, v17
	v_mov_b32_e32 v156, 0x358637bd
	s_mov_b32 s40, 0x800000
	s_movk_i32 s41, 0x2c00
	s_barrier
	v_readlane_b32 s1, v234, 13
	s_branch .LBB0_497

.LBB0_511:
	v_readlane_b32 s0, v234, 12
	v_writelane_b32 v233, s52, 12
	s_abs_i32 s52, s0
	v_cvt_f32_u32_e32 v0, s52
	s_sub_i32 s0, 0, s52
	v_readlane_b32 s1, v234, 13
	v_writelane_b32 v233, s50, 13
	v_rcp_iflag_f32_e32 v0, v0
	s_nop 0
	v_writelane_b32 v233, s51, 14
	v_mul_f32_e32 v0, 0x4f7ffffe, v0
	v_cvt_u32_f32_e32 v0, v0
	s_nop 0
	v_readfirstlane_b32 s53, v0
	s_mul_i32 s0, s0, s53
	s_mul_hi_u32 s0, s53, s0
	s_add_i32 s53, s53, s0
	s_mul_hi_u32 s0, s53, 0x5ac
	s_mul_i32 s0, s0, s52
	s_sub_i32 s0, 0x5ac, s0
	s_sub_i32 s1, s0, s52
	s_cmp_ge_u32 s0, s52
	s_cselect_b32 s0, s1, s0
	s_sub_i32 s1, s0, s52
	s_cmp_ge_u32 s0, s52
	s_movk_i32 s5, 0xf2
	s_cmp_eq_u32 s5, 0
	s_cselect_b64 s[0:1], -1, 0
	s_cmp_lt_i32 s4, s5
	s_cselect_b64 s[2:3], -1, 0
	s_or_b64 s[0:1], s[0:1], s[2:3]
	s_and_b64 vcc, exec, s[0:1]
	s_cbranch_vccnz .LBB0_931
	v_readlane_b32 s2, v234, 14
	v_readlane_b32 s3, v234, 12
	v_readfirstlane_b32 s0, v183
	s_sub_i32 s2, s2, s5
	s_sub_i32 s3, s3, s5
	s_lshl_b32 s2, s2, 3
	s_lshr_b32 s0, s0, 6
	s_add_i32 s4, s2, s0
	s_lshl_b32 s33, s3, 3
	s_cmp_ge_u32 s4, 0x1076
	s_cbranch_scc1 .LBB0_931
	v_readlane_b32 s30, v234, 2
	v_readlane_b32 s31, v234, 3
	v_and_b32_e32 v176, 7, v183
	v_bfe_u32 v185, v183, 3, 3
	v_lshlrev_b32_e32 v177, 4, v185
	v_lshlrev_b32_e32 v186, 4, v176
	s_cmp_lt_u32 s4, 0x1076
	s_cbranch_scc1 .Lcv1_p0_go
	s_mov_b32 s22, 0
	s_branch .Lcv1_p0_end

.Lcv1_p0_seg1:
	s_add_u32 s34, s4, 0xcaa
	s_mul_i32 s39, s34, 18002
	s_lshr_b32 s39, s39, 22
	s_mul_i32 s40, s39, 233
	s_sub_u32 s40, s34, s40
	v_readlane_b32 s0, v234, 48
	v_readlane_b32 s1, v234, 49
	s_mul_i32 s2, s39, 0x3a2800
	s_lshl_b32 s3, s40, 8
	s_add_u32 s2, s2, s3
	s_add_u32 s0, s0, s2
	s_addc_u32 s1, s1, 0
	s_mov_b32 s41, 0xe8a0
	s_mov_b32 s42, 0x74500
	s_lshl_b32 s2, s40, 18
	s_lshl_b32 s3, s39, 7
	s_add_u32 s2, s2, s3
	s_add_u32 s2, s2, 0x43d8000
	s_add_u32 s16, s30, s2
	s_addc_u32 s17, s31, 0
	s_mov_b32 s20, 0x1000
	s_mov_b32 s21, 0x4000
	s_lshl_b32 s23, s40, 6
	s_mov_b64 s[46:47], -1
	s_cmp_eq_u32 s40, 232
	s_cbranch_scc0 .Lcv1_p0_full1
	s_mov_b64 s[46:47], 0xffff

.Lcv1_p0_end:
	s_cmp_lt_u32 s4, 0x1076
	s_cbranch_scc1 .Lcv1_p1_go
	s_mov_b32 s28, 0
	s_branch .Lcv1_p1_end

.Lcv1_p1_seg1:
	s_add_u32 s34, s4, 0xcaa
	s_mul_i32 s39, s34, 18002
	s_lshr_b32 s39, s39, 22
	s_mul_i32 s40, s39, 233
	s_sub_u32 s40, s34, s40
	v_readlane_b32 s0, v234, 48
	v_readlane_b32 s1, v234, 49
	s_mul_i32 s2, s39, 0x3a2800
	s_lshl_b32 s3, s40, 8
	s_add_u32 s2, s2, s3
	s_add_u32 s0, s0, s2
	s_addc_u32 s1, s1, 0
	s_mov_b32 s41, 0xe8a0
	s_mov_b32 s42, 0x74500
	s_lshl_b32 s2, s40, 18
	s_lshl_b32 s3, s39, 7
	s_add_u32 s2, s2, s3
	s_add_u32 s2, s2, 0x43d8000
	s_add_u32 s24, s30, s2
	s_addc_u32 s25, s31, 0
	s_mov_b32 s26, 0x1000
	s_mov_b32 s27, 0x4000
	s_lshl_b32 s29, s40, 6
	s_mov_b64 s[46:47], -1
	s_cmp_eq_u32 s40, 232
	s_cbranch_scc0 .Lcv1_p1_full1
	s_mov_b64 s[46:47], 0xffff

.Lcv1_pa_plain:
	v_pk_mul_f32 v[0:1], v[0:1], v[128:129] op_sel_hi:[1,0]
	v_pk_mul_f32 v[2:3], v[2:3], v[128:129] op_sel_hi:[1,0]
	v_pk_mul_f32 v[4:5], v[4:5], v[128:129] op_sel_hi:[1,0]
	v_pk_mul_f32 v[6:7], v[6:7], v[128:129] op_sel_hi:[1,0]
	v_pk_mul_f32 v[8:9], v[8:9], v[128:129] op_sel:[0,1]
	v_pk_mul_f32 v[10:11], v[10:11], v[128:129] op_sel:[0,1]
	v_pk_mul_f32 v[12:13], v[12:13], v[128:129] op_sel:[0,1]
	v_pk_mul_f32 v[14:15], v[14:15], v[128:129] op_sel:[0,1]
	v_pk_mul_f32 v[16:17], v[16:17], v[130:131] op_sel_hi:[1,0]
	v_pk_mul_f32 v[18:19], v[18:19], v[130:131] op_sel_hi:[1,0]
	v_pk_mul_f32 v[20:21], v[20:21], v[130:131] op_sel_hi:[1,0]
	v_pk_mul_f32 v[22:23], v[22:23], v[130:131] op_sel_hi:[1,0]
	v_pk_mul_f32 v[24:25], v[24:25], v[130:131] op_sel:[0,1]
	v_pk_mul_f32 v[26:27], v[26:27], v[130:131] op_sel:[0,1]
	v_pk_mul_f32 v[28:29], v[28:29], v[130:131] op_sel:[0,1]
	v_pk_mul_f32 v[30:31], v[30:31], v[130:131] op_sel:[0,1]
	v_pk_mul_f32 v[32:33], v[32:33], v[132:133] op_sel_hi:[1,0]
	v_pk_mul_f32 v[34:35], v[34:35], v[132:133] op_sel_hi:[1,0]
	v_pk_mul_f32 v[36:37], v[36:37], v[132:133] op_sel_hi:[1,0]
	v_pk_mul_f32 v[38:39], v[38:39], v[132:133] op_sel_hi:[1,0]
	v_pk_mul_f32 v[40:41], v[40:41], v[132:133] op_sel:[0,1]
	v_pk_mul_f32 v[42:43], v[42:43], v[132:133] op_sel:[0,1]
	v_pk_mul_f32 v[44:45], v[44:45], v[132:133] op_sel:[0,1]
	v_pk_mul_f32 v[46:47], v[46:47], v[132:133] op_sel:[0,1]
	v_pk_mul_f32 v[48:49], v[48:49], v[134:135] op_sel_hi:[1,0]
	v_pk_mul_f32 v[50:51], v[50:51], v[134:135] op_sel_hi:[1,0]
	v_pk_mul_f32 v[52:53], v[52:53], v[134:135] op_sel_hi:[1,0]
	v_pk_mul_f32 v[54:55], v[54:55], v[134:135] op_sel_hi:[1,0]
	v_pk_mul_f32 v[56:57], v[56:57], v[134:135] op_sel:[0,1]
	v_pk_mul_f32 v[58:59], v[58:59], v[134:135] op_sel:[0,1]
	v_pk_mul_f32 v[60:61], v[60:61], v[134:135] op_sel:[0,1]
	v_pk_mul_f32 v[62:63], v[62:63], v[134:135] op_sel:[0,1]
	v_cvt_pk_bf16_f32 v144, v0, v8
	v_cvt_pk_bf16_f32 v145, v16, v24
	v_cvt_pk_bf16_f32 v146, v32, v40
	v_cvt_pk_bf16_f32 v147, v48, v56
	global_store_dwordx4 v179, v[144:147], s[16:17]
	v_cvt_pk_bf16_f32 v148, v1, v9
	v_cvt_pk_bf16_f32 v149, v17, v25
	v_cvt_pk_bf16_f32 v150, v33, v41
	v_cvt_pk_bf16_f32 v151, v49, v57
	s_add_u32 s16, s16, s20
	s_addc_u32 s17, s17, 0
	global_store_dwordx4 v179, v[148:151], s[16:17]
	v_cvt_pk_bf16_f32 v152, v2, v10
	v_cvt_pk_bf16_f32 v153, v18, v26
	v_cvt_pk_bf16_f32 v154, v34, v42
	v_cvt_pk_bf16_f32 v155, v50, v58
	s_add_u32 s16, s16, s20
	s_addc_u32 s17, s17, 0
	global_store_dwordx4 v179, v[152:155], s[16:17]
	v_cvt_pk_bf16_f32 v156, v3, v11
	v_cvt_pk_bf16_f32 v157, v19, v27
	v_cvt_pk_bf16_f32 v158, v35, v43
	v_cvt_pk_bf16_f32 v159, v51, v59
	s_add_u32 s16, s16, s20
	s_addc_u32 s17, s17, 0
	global_store_dwordx4 v179, v[156:159], s[16:17]
	s_mov_b64 exec, s[48:49]
	v_cvt_pk_bf16_f32 v160, v4, v12
	v_cvt_pk_bf16_f32 v161, v20, v28
	v_cvt_pk_bf16_f32 v162, v36, v44
	v_cvt_pk_bf16_f32 v163, v52, v60
	s_mul_i32 s2, s20, 29
	s_add_u32 s16, s16, s2
	s_addc_u32 s17, s17, 0
	global_store_dwordx4 v184, v[160:163], s[16:17]
	v_cvt_pk_bf16_f32 v164, v5, v13
	v_cvt_pk_bf16_f32 v165, v21, v29
	v_cvt_pk_bf16_f32 v166, v37, v45
	v_cvt_pk_bf16_f32 v167, v53, v61
	s_add_u32 s16, s16, s20
	s_addc_u32 s17, s17, 0
	global_store_dwordx4 v184, v[164:167], s[16:17]
	v_cvt_pk_bf16_f32 v168, v6, v14
	v_cvt_pk_bf16_f32 v169, v22, v30
	v_cvt_pk_bf16_f32 v170, v38, v46
	v_cvt_pk_bf16_f32 v171, v54, v62
	s_add_u32 s16, s16, s20
	s_addc_u32 s17, s17, 0
	global_store_dwordx4 v184, v[168:171], s[16:17]
	v_cvt_pk_bf16_f32 v172, v7, v15
	v_cvt_pk_bf16_f32 v173, v23, v31
	v_cvt_pk_bf16_f32 v174, v39, v47
	v_cvt_pk_bf16_f32 v175, v55, v63
	s_add_u32 s16, s16, s20
	s_addc_u32 s17, s17, 0
	global_store_dwordx4 v184, v[172:175], s[16:17]
	s_mov_b64 exec, -1
	s_cmp_lt_u32 s4, 0x1076
	s_cbranch_scc1 .Lcv1_la_go
	s_mov_b32 s22, 0
	s_branch .Lcv1_la_end

.Lcv1_pb_plain:
	v_pk_mul_f32 v[64:65], v[64:65], v[136:137] op_sel_hi:[1,0]
	v_pk_mul_f32 v[66:67], v[66:67], v[136:137] op_sel_hi:[1,0]
	v_pk_mul_f32 v[68:69], v[68:69], v[136:137] op_sel_hi:[1,0]
	v_pk_mul_f32 v[70:71], v[70:71], v[136:137] op_sel_hi:[1,0]
	v_pk_mul_f32 v[72:73], v[72:73], v[136:137] op_sel:[0,1]
	v_pk_mul_f32 v[74:75], v[74:75], v[136:137] op_sel:[0,1]
	v_pk_mul_f32 v[76:77], v[76:77], v[136:137] op_sel:[0,1]
	v_pk_mul_f32 v[78:79], v[78:79], v[136:137] op_sel:[0,1]
	v_pk_mul_f32 v[80:81], v[80:81], v[138:139] op_sel_hi:[1,0]
	v_pk_mul_f32 v[82:83], v[82:83], v[138:139] op_sel_hi:[1,0]
	v_pk_mul_f32 v[84:85], v[84:85], v[138:139] op_sel_hi:[1,0]
	v_pk_mul_f32 v[86:87], v[86:87], v[138:139] op_sel_hi:[1,0]
	v_pk_mul_f32 v[88:89], v[88:89], v[138:139] op_sel:[0,1]
	v_pk_mul_f32 v[90:91], v[90:91], v[138:139] op_sel:[0,1]
	v_pk_mul_f32 v[92:93], v[92:93], v[138:139] op_sel:[0,1]
	v_pk_mul_f32 v[94:95], v[94:95], v[138:139] op_sel:[0,1]
	v_pk_mul_f32 v[96:97], v[96:97], v[140:141] op_sel_hi:[1,0]
	v_pk_mul_f32 v[98:99], v[98:99], v[140:141] op_sel_hi:[1,0]
	v_pk_mul_f32 v[100:101], v[100:101], v[140:141] op_sel_hi:[1,0]
	v_pk_mul_f32 v[102:103], v[102:103], v[140:141] op_sel_hi:[1,0]
	v_pk_mul_f32 v[104:105], v[104:105], v[140:141] op_sel:[0,1]
	v_pk_mul_f32 v[106:107], v[106:107], v[140:141] op_sel:[0,1]
	v_pk_mul_f32 v[108:109], v[108:109], v[140:141] op_sel:[0,1]
	v_pk_mul_f32 v[110:111], v[110:111], v[140:141] op_sel:[0,1]
	v_pk_mul_f32 v[112:113], v[112:113], v[142:143] op_sel_hi:[1,0]
	v_pk_mul_f32 v[114:115], v[114:115], v[142:143] op_sel_hi:[1,0]
	v_pk_mul_f32 v[116:117], v[116:117], v[142:143] op_sel_hi:[1,0]
	v_pk_mul_f32 v[118:119], v[118:119], v[142:143] op_sel_hi:[1,0]
	v_pk_mul_f32 v[120:121], v[120:121], v[142:143] op_sel:[0,1]
	v_pk_mul_f32 v[122:123], v[122:123], v[142:143] op_sel:[0,1]
	v_pk_mul_f32 v[124:125], v[124:125], v[142:143] op_sel:[0,1]
	v_pk_mul_f32 v[126:127], v[126:127], v[142:143] op_sel:[0,1]
	v_cvt_pk_bf16_f32 v144, v64, v72
	v_cvt_pk_bf16_f32 v145, v80, v88
	v_cvt_pk_bf16_f32 v146, v96, v104
	v_cvt_pk_bf16_f32 v147, v112, v120
	global_store_dwordx4 v179, v[144:147], s[24:25]
	v_cvt_pk_bf16_f32 v148, v65, v73
	v_cvt_pk_bf16_f32 v149, v81, v89
	v_cvt_pk_bf16_f32 v150, v97, v105
	v_cvt_pk_bf16_f32 v151, v113, v121
	s_add_u32 s24, s24, s26
	s_addc_u32 s25, s25, 0
	global_store_dwordx4 v179, v[148:151], s[24:25]
	v_cvt_pk_bf16_f32 v152, v66, v74
	v_cvt_pk_bf16_f32 v153, v82, v90
	v_cvt_pk_bf16_f32 v154, v98, v106
	v_cvt_pk_bf16_f32 v155, v114, v122
	s_add_u32 s24, s24, s26
	s_addc_u32 s25, s25, 0
	global_store_dwordx4 v179, v[152:155], s[24:25]
	v_cvt_pk_bf16_f32 v156, v67, v75
	v_cvt_pk_bf16_f32 v157, v83, v91
	v_cvt_pk_bf16_f32 v158, v99, v107
	v_cvt_pk_bf16_f32 v159, v115, v123
	s_add_u32 s24, s24, s26
	s_addc_u32 s25, s25, 0
	global_store_dwordx4 v179, v[156:159], s[24:25]
	s_mov_b64 exec, s[48:49]
	v_cvt_pk_bf16_f32 v160, v68, v76
	v_cvt_pk_bf16_f32 v161, v84, v92
	v_cvt_pk_bf16_f32 v162, v100, v108
	v_cvt_pk_bf16_f32 v163, v116, v124
	s_mul_i32 s2, s26, 29
	s_add_u32 s24, s24, s2
	s_addc_u32 s25, s25, 0
	global_store_dwordx4 v184, v[160:163], s[24:25]
	v_cvt_pk_bf16_f32 v164, v69, v77
	v_cvt_pk_bf16_f32 v165, v85, v93
	v_cvt_pk_bf16_f32 v166, v101, v109
	v_cvt_pk_bf16_f32 v167, v117, v125
	s_add_u32 s24, s24, s26
	s_addc_u32 s25, s25, 0
	global_store_dwordx4 v184, v[164:167], s[24:25]
	v_cvt_pk_bf16_f32 v168, v70, v78
	v_cvt_pk_bf16_f32 v169, v86, v94
	v_cvt_pk_bf16_f32 v170, v102, v110
	v_cvt_pk_bf16_f32 v171, v118, v126
	s_add_u32 s24, s24, s26
	s_addc_u32 s25, s25, 0
	global_store_dwordx4 v184, v[168:171], s[24:25]
	v_cvt_pk_bf16_f32 v172, v71, v79
	v_cvt_pk_bf16_f32 v173, v87, v95
	v_cvt_pk_bf16_f32 v174, v103, v111
	v_cvt_pk_bf16_f32 v175, v119, v127
	s_add_u32 s24, s24, s26
	s_addc_u32 s25, s25, 0
	global_store_dwordx4 v184, v[172:175], s[24:25]
	s_mov_b64 exec, -1
	s_cmp_lt_u32 s4, 0x1076
	s_cbranch_scc1 .Lcv1_lb_go
	s_mov_b32 s28, 0
	s_branch .Lcv1_lb_end

.LBB0_2301:
	s_lshl_b32 s1, s8, 5
	s_mov_b64 s[8:9], 0x80
	s_and_b32 s14, s1, 0x60
	s_add_i32 m0, s30, 0x18000
	v_lshl_add_u64 v[6:7], v[6:7], 0, s[8:9]
	s_lshl_b32 s11, s10, 13
	s_lshl_b32 s15, s14, 7
	s_waitcnt vmcnt(2)
	s_barrier
	global_load_lds_dwordx4 v[6:7], off
	v_lshl_add_u64 v[4:5], v[4:5], 0, s[8:9]
	s_add_i32 m0, s30, 0x1a000
	s_add_i32 s36, s30, 0x8000
	s_add_i32 s37, s30, 0xa000
	global_load_lds_dwordx4 v[4:5], off
	v_lshl_add_u64 v[0:1], v[0:1], 0, s[8:9]
	s_mov_b32 m0, s36
	s_add_u32 s12, s22, 0x80080
	global_load_lds_dwordx4 v[0:1], off
	v_lshl_add_u64 v[0:1], v[2:3], 0, s[8:9]
	s_mov_b32 m0, s37
	s_addc_u32 s13, s23, 0
	global_load_lds_dwordx4 v[0:1], off
	s_add_i32 m0, s30, 0x1c000
	v_lshl_add_u64 v[0:1], s[12:13], 0, v[130:131]
	global_load_lds_dwordx4 v[0:1], off
	v_lshl_add_u64 v[0:1], s[12:13], 0, v[134:135]
	s_add_i32 m0, s30, 0x1e000
	s_cmpk_lt_u32 s7, 0x100
	global_load_lds_dwordx4 v[0:1], off
	v_lshrrev_b32_e32 v1, 1, v8
	v_and_b32_e32 v1, 24, v1
	v_and_b32_e32 v0, 15, v8
	v_lshlrev_b32_e32 v2, 1, v1
	v_lshl_or_b32 v152, s10, 6, v0
	v_lshl_or_b32 v0, v0, 6, v2
	v_lshlrev_b32_e32 v2, 2, v8
	v_and_b32_e32 v2, 32, v2
	v_bitop3_b32 v3, v0, s11, v2 bitop3:0xde
	v_bitop3_b32 v153, v0, s15, v2 bitop3:0xde
	v_lshlrev_b32_e32 v0, 15, v9
	v_and_b32_e32 v0, 0xffff0000, v0
	v_or_b32_e32 v154, s14, v1
	v_lshl_add_u32 v0, v10, 12, v0
	v_and_b32_e32 v1, 1, v9
	v_lshl_or_b32 v0, v1, 6, v0
	v_lshl_add_u32 v136, v11, 1, v0
	v_lshlrev_b32_e32 v0, 15, v12
	v_and_b32_e32 v0, 0xffff0000, v0
	s_waitcnt vmcnt(6)
	v_lshl_add_u32 v0, v13, 12, v0
	v_and_b32_e32 v1, 1, v12
	s_sext_i32_i16 s1, s6
	s_cselect_b64 s[10:11], -1, 0
	v_readlane_b32 s6, v234, 12
	v_lshl_or_b32 v0, v1, 6, v0
	s_add_i32 s40, 0, 0x10000
	s_add_i32 s41, 0, 0x14000
	s_ashr_i32 s38, s6, 31
	s_movk_i32 s39, 0xf2
	v_mov_b32_e32 v137, v131
	v_lshl_add_u32 v138, v14, 1, v0
	v_mov_b32_e32 v139, v131
	v_mov_b64_e32 v[140:141], 0x5ac
	v_mov_b64_e32 v[142:143], 0x5ab
	v_add_u32_e32 v155, s40, v153
	v_add_u32_e32 v156, s41, v153
	v_add_u32_e32 v157, 0, v3
	v_mov_b32_e32 v158, 0x358637bd
	s_mov_b32 s42, 0x800000
	s_movk_i32 s43, 0x2c00
	s_barrier
	v_readlane_b32 s7, v234, 13
	s_branch .LBB0_2304

.LBB0_2318:
	v_readlane_b32 s3, v234, 12
	s_movk_i32 s5, 0xf2
	v_readlane_b32 s2, v234, 14
	s_cmp_eq_u32 s5, 0
	s_cbranch_scc1 .Lcv3_exit
	s_cmp_lt_i32 s2, s5
	s_cbranch_scc1 .Lcv3_exit
	v_readlane_b32 s2, v234, 14
	v_readlane_b32 s3, v234, 12
	v_readfirstlane_b32 s0, v183
	s_sub_i32 s2, s2, s5
	s_sub_i32 s3, s3, s5
	s_lshl_b32 s2, s2, 3
	s_lshr_b32 s0, s0, 6
	s_add_i32 s4, s2, s0
	s_lshl_b32 s33, s3, 3
	s_cmp_ge_u32 s4, 0xb00
	s_cbranch_scc1 .Lcv3_exit
	v_readlane_b32 s30, v234, 2
	v_readlane_b32 s31, v234, 3
	v_and_b32_e32 v220, 7, v183
	v_bfe_u32 v224, v183, 3, 3
	v_lshlrev_b32_e32 v221, 4, v224
	v_lshlrev_b32_e32 v225, 4, v220
	s_cmp_lt_u32 s4, 0xb00
	s_cbranch_scc1 .Lcv3_p0_go
	s_mov_b32 s22, 0
	s_branch .Lcv3_p0_end
